# SSD output stage: batch u16 reads + lockstep bpermute reductions; HGRN sts b32 pairing; phase0 scale reuse; barrier ladder
# baseline (speedup 1.0000x reference)
.LBB0_273:
	s_or_b64 exec, exec, s[84:85]
	ds_read_b32 v43, v132
	ds_read_b32 v87, v133
	s_waitcnt vmcnt(20)
	v_lshlrev_b32_e32 v84, 16, v84
	s_mov_b32 s0, 0x25f92000
	s_mov_b64 s[84:85], 0x800
	s_waitcnt lgkmcnt(1)
	v_sub_f32_e32 v44, v44, v43
	v_mul_f32_e32 v44, 0x3fb8aa3b, v44
	v_exp_f32_e32 v44, v44
	s_nop 0
	v_mul_f32_e32 v38, v38, v44
	s_waitcnt lgkmcnt(0)
	v_mul_f32_e32 v38, v87, v38
	v_cndmask_b32_e64 v38, v38, 0, s[36:37]
	v_cvt_pk_bf16_f32 v38, v38, v38
	ds_write_b16 v128, v38 offset:32
	v_sub_f32_e32 v38, v45, v43
	v_mul_f32_e32 v38, 0x3fb8aa3b, v38
	v_exp_f32_e32 v38, v38
	s_nop 0
	v_mul_f32_e32 v38, v39, v38
	v_mul_f32_e32 v38, v87, v38
	v_cndmask_b32_e64 v38, v38, 0, s[38:39]
	v_cvt_pk_bf16_f32 v38, v38, v38
	ds_write_b16 v129, v38 offset:32
	v_sub_f32_e32 v38, v85, v43
	v_mul_f32_e32 v38, 0x3fb8aa3b, v38
	v_exp_f32_e32 v38, v38
	s_nop 0
	v_mul_f32_e32 v38, v40, v38
	v_mul_f32_e32 v38, v87, v38
	v_cndmask_b32_e64 v38, v38, 0, s[40:41]
	v_cvt_pk_bf16_f32 v38, v38, v38
	ds_write_b16 v130, v38 offset:32
	v_sub_f32_e32 v38, v42, v43
	v_mul_f32_e32 v38, 0x3fb8aa3b, v38
	v_exp_f32_e32 v38, v38
	s_nop 0
	v_mul_f32_e32 v38, v41, v38
	v_mul_f32_e32 v38, v87, v38
	v_cndmask_b32_e64 v38, v38, 0, s[42:43]
	v_cvt_pk_bf16_f32 v38, v38, v38
	ds_write_b16 v131, v38 offset:32
	s_waitcnt lgkmcnt(0)
	s_barrier
	ds_read_b128 v[38:41], v90
	ds_read_b128 v[42:45], v134
	ds_read_b128 v[166:169], v110
	s_waitcnt lgkmcnt(1)
	v_mfma_f32_16x16x32_bf16 v[42:45], v[38:41], v[42:45], 0
	s_waitcnt lgkmcnt(0)
	v_mfma_f32_16x16x32_bf16 v[38:41], v[38:41], v[166:169], 0
	ds_read_b128 v[166:169], v90 offset:64
	ds_read_b128 v[188:191], v134 offset:64
	s_waitcnt lgkmcnt(0)
	v_mfma_f32_16x16x32_bf16 v[42:45], v[166:169], v[188:191], v[42:45]
	ds_read_b128 v[188:191], v110 offset:64
	s_waitcnt lgkmcnt(0)
	v_mfma_f32_16x16x32_bf16 v[38:41], v[166:169], v[188:191], v[38:41]
	ds_read_b128 v[166:169], v90 offset:128
	ds_read_b128 v[188:191], v134 offset:128
	s_waitcnt lgkmcnt(0)
	v_mfma_f32_16x16x32_bf16 v[42:45], v[166:169], v[188:191], v[42:45]
	ds_read_b128 v[188:191], v110 offset:128
	s_waitcnt lgkmcnt(0)
	v_mfma_f32_16x16x32_bf16 v[38:41], v[166:169], v[188:191], v[38:41]
	ds_read_b128 v[166:169], v90 offset:192
	ds_read_b128 v[188:191], v134 offset:192
	s_waitcnt lgkmcnt(0)
	v_mfma_f32_16x16x32_bf16 v[42:45], v[166:169], v[188:191], v[42:45]
	ds_read_b128 v[188:191], v110 offset:192
	s_waitcnt lgkmcnt(0)
	v_mfma_f32_16x16x32_bf16 v[38:41], v[166:169], v[188:191], v[38:41]
	ds_read2_b32 v[166:167], v105 offset1:1
	s_waitcnt lgkmcnt(0)
	v_mul_f32_e32 v85, 0x3fb8aa3b, v166
	v_exp_f32_e32 v170, v85
	v_mul_f32_e32 v85, 0x3fb8aa3b, v167
	ds_read2_b32 v[166:167], v107 offset1:1
	v_exp_f32_e32 v171, v85
	s_waitcnt lgkmcnt(0)
	v_mul_f32_e32 v85, 0x3fb8aa3b, v166
	v_exp_f32_e32 v192, v85
	v_mul_f32_e32 v85, 0x3fb8aa3b, v167
	v_exp_f32_e32 v193, v85
	ds_read_b128 v[166:169], v91
	ds_read_b128 v[188:191], v135 offset:53248
	v_pk_mul_f32 v[42:43], v[42:43], v[170:171]
	v_pk_mul_f32 v[38:39], v[38:39], v[170:171]
	v_pk_mul_f32 v[44:45], v[44:45], v[192:193]
	v_pk_mul_f32 v[40:41], v[40:41], v[192:193]
	s_waitcnt lgkmcnt(0)
	v_mfma_f32_16x16x32_bf16 v[42:45], v[166:169], v[188:191], v[42:45]
	ds_read_b128 v[188:191], v111 offset:53248
	s_waitcnt lgkmcnt(0)
	v_mfma_f32_16x16x32_bf16 v[38:41], v[166:169], v[188:191], v[38:41]
	ds_read_b128 v[166:169], v91 offset:64
	ds_read_b128 v[188:191], v136 offset:53248
	ds_read_u16 v85, v137 offset:53248
	ds_read_u16 v194, v138 offset:53248
	ds_read_u16 v195, v139 offset:53248
	ds_read_u16 v196, v140 offset:53248
	ds_read_u16 v197, v113 offset:53248
	ds_read_u16 v198, v114 offset:53248
	ds_read_u16 v199, v115 offset:53248
	ds_read_u16 v200, v116 offset:53248
	s_waitcnt lgkmcnt(0)
	v_lshlrev_b32_e32 v85, 16, v85
	v_mfma_f32_16x16x32_bf16 v[42:45], v[166:169], v[188:191], v[42:45]
	ds_read_b128 v[188:191], v112 offset:53248
	s_waitcnt lgkmcnt(0)
	v_mfma_f32_16x16x32_bf16 v[38:41], v[166:169], v[188:191], v[38:41]
	v_lshl_add_u64 v[166:167], s[50:51], 0, v[72:73]
	s_nop 3
	v_fma_f32 v42, v51, v85, v42
	v_mul_f32_e32 v85, 0xbfb8aa3b, v84
	v_exp_f32_e32 v85, v85
	v_add_co_u32_e32 v168, vcc, s0, v166
	s_mov_b64 s[0:1], 0x1000
	v_add_f32_e32 v85, 1.0, v85
	v_rcp_f32_e32 v85, v85
	v_addc_co_u32_e32 v169, vcc, 0, v167, vcc
	v_mul_f32_e32 v84, v85, v84
	v_mul_f32_e32 v144, v84, v42
	v_cvt_pk_bf16_f32 v42, v144, v144
	global_store_short v[168:169], v42, off offset:-4096
	v_mov_b32_e32 v42, v194
	v_lshl_add_u64 v[84:85], v[82:83], 0, s[56:57]
	s_waitcnt lgkmcnt(0)
	v_lshlrev_b32_e32 v42, 16, v42
	v_fma_f32 v42, v51, v42, v43
	s_waitcnt vmcnt(20)
	v_lshlrev_b32_e32 v43, 16, v86
	v_mul_f32_e32 v86, 0xbfb8aa3b, v43
	v_exp_f32_e32 v86, v86
	s_nop 0
	v_add_f32_e32 v86, 1.0, v86
	v_rcp_f32_e32 v86, v86
	s_nop 0
	v_mul_f32_e32 v43, v86, v43
	v_mul_f32_e32 v165, v43, v42
	v_cvt_pk_bf16_f32 v42, v165, v165
	global_store_short v[168:169], v42, off
	v_mov_b32_e32 v42, v195
	s_waitcnt vmcnt(20)
	v_lshlrev_b32_e32 v43, 16, v164
	v_lshl_add_u64 v[86:87], v[84:85], 0, s[84:85]
	v_or_b32_e32 v86, v86, v66
	s_waitcnt lgkmcnt(0)
	v_lshlrev_b32_e32 v42, 16, v42
	v_fma_f32 v42, v51, v42, v44
	v_mul_f32_e32 v44, 0xbfb8aa3b, v43
	v_exp_f32_e32 v44, v44
	s_nop 0
	v_add_f32_e32 v44, 1.0, v44
	v_rcp_f32_e32 v44, v44
	s_nop 0
	v_mul_f32_e32 v43, v44, v43
	v_mul_f32_e32 v164, v43, v42
	v_lshl_add_u64 v[42:43], v[84:85], 0, s[0:1]
	s_mov_b32 s0, 0x25f94000
	v_add_co_u32_e32 v166, vcc, s0, v166
	v_cvt_pk_bf16_f32 v44, v164, v164
	s_mov_b64 s[0:1], 0x1800
	s_nop 0
	v_addc_co_u32_e32 v167, vcc, 0, v167, vcc
	global_store_short v[166:167], v44, off offset:-4096
	v_mov_b32_e32 v44, v196
	v_or_b32_e32 v42, v42, v66
	v_lshl_add_u64 v[42:43], v[42:43], 1, s[74:75]
	s_waitcnt lgkmcnt(0)
	v_lshlrev_b32_e32 v44, 16, v44
	v_fmac_f32_e32 v45, v51, v44
	s_waitcnt vmcnt(20)
	v_lshlrev_b32_e32 v44, 16, v163
	v_mul_f32_e32 v145, 0xbfb8aa3b, v44
	v_exp_f32_e32 v145, v145
	s_nop 0
	v_add_f32_e32 v145, 1.0, v145
	v_rcp_f32_e32 v145, v145
	s_nop 0
	v_mul_f32_e32 v44, v145, v44
	v_mul_f32_e32 v163, v44, v45
	v_cvt_pk_bf16_f32 v145, v163, v163
	global_store_short v[166:167], v145, off
	v_mov_b32_e32 v145, v197
	v_lshl_add_u64 v[44:45], v[84:85], 0, s[0:1]
	v_or_b32_e32 v84, v84, v66
	v_lshl_add_u64 v[84:85], v[84:85], 1, s[74:75]
	v_or_b32_e32 v44, v44, v66
	s_waitcnt lgkmcnt(0)
	v_lshlrev_b32_e32 v145, 16, v145
	v_fma_f32 v38, v51, v145, v38
	s_waitcnt vmcnt(20)
	v_lshlrev_b32_e32 v145, 16, v160
	v_mul_f32_e32 v146, 0xbfb8aa3b, v145
	v_exp_f32_e32 v146, v146
	s_nop 0
	v_add_f32_e32 v146, 1.0, v146
	v_rcp_f32_e32 v146, v146
	s_nop 0
	v_mul_f32_e32 v145, v146, v145
	v_mul_f32_e32 v38, v145, v38
	v_cvt_pk_bf16_f32 v145, v38, v38
	global_store_short v[84:85], v145, off
	v_mul_f32_e32 v145, v38, v38
	v_mov_b32_e32 v38, v198
	v_fmac_f32_e32 v145, v144, v144
	s_waitcnt lgkmcnt(0)
	v_lshlrev_b32_e32 v38, 16, v38
	v_fma_f32 v38, v51, v38, v39
	s_waitcnt vmcnt(18)
	v_lshlrev_b32_e32 v39, 16, v154
	v_mul_f32_e32 v84, 0xbfb8aa3b, v39
	v_exp_f32_e32 v84, v84
	s_nop 0
	v_add_f32_e32 v84, 1.0, v84
	v_rcp_f32_e32 v84, v84
	s_nop 0
	v_mul_f32_e32 v39, v84, v39
	v_mul_f32_e32 v38, v39, v38
	v_cvt_pk_bf16_f32 v39, v38, v38
	v_lshl_add_u64 v[84:85], v[86:87], 1, s[74:75]
	global_store_short v[84:85], v39, off
	v_mov_b32_e32 v39, v199
	s_waitcnt lgkmcnt(0)
	v_lshlrev_b32_e32 v39, 16, v39
	v_fma_f32 v39, v51, v39, v40
	v_lshlrev_b32_e32 v40, 16, v153
	v_mul_f32_e32 v84, 0xbfb8aa3b, v40
	v_exp_f32_e32 v84, v84
	s_nop 0
	v_add_f32_e32 v84, 1.0, v84
	v_rcp_f32_e32 v84, v84
	s_nop 0
	v_mul_f32_e32 v40, v84, v40
	v_mul_f32_e32 v39, v40, v39
	v_cvt_pk_bf16_f32 v40, v39, v39
	global_store_short v[42:43], v40, off
	v_mov_b32_e32 v40, v200
	s_waitcnt lgkmcnt(0)
	v_lshlrev_b32_e32 v40, 16, v40
	v_fmac_f32_e32 v41, v51, v40
	v_lshlrev_b32_e32 v40, 16, v141
	v_mul_f32_e32 v42, 0xbfb8aa3b, v40
	v_exp_f32_e32 v42, v42
	s_nop 0
	v_add_f32_e32 v42, 1.0, v42
	v_rcp_f32_e32 v42, v42
	s_nop 0
	v_mul_f32_e32 v40, v42, v40
	v_lshl_add_u64 v[42:43], v[44:45], 1, s[74:75]
	v_mul_f32_e32 v40, v40, v41
	v_cvt_pk_bf16_f32 v41, v40, v40
	global_store_short v[42:43], v41, off
	v_and_b32_e32 v42, 64, v177
	v_xor_b32_e32 v41, 1, v177
	v_add_u32_e32 v44, 64, v42
	v_cmp_lt_i32_e32 vcc, v41, v44
	v_xor_b32_e32 v42, 2, v177
	v_xor_b32_e32 v43, 4, v177
	v_cndmask_b32_e32 v41, v177, v41, vcc
	v_cmp_lt_i32_e32 vcc, v42, v44
	v_xor_b32_e32 v45, 8, v177
	v_lshlrev_b32_e32 v41, 2, v41
	v_cndmask_b32_e32 v42, v177, v42, vcc
	v_cmp_lt_i32_e32 vcc, v43, v44
	v_lshlrev_b32_e32 v42, 2, v42
	s_nop 0
	v_cndmask_b32_e32 v43, v177, v43, vcc
	v_cmp_lt_i32_e32 vcc, v45, v44
	v_lshlrev_b32_e32 v43, 2, v43
	s_nop 0
	v_cndmask_b32_e32 v44, v177, v45, vcc
	v_lshlrev_b32_e32 v44, 2, v44
	v_mul_f32_e32 v201, v38, v38
	v_fmac_f32_e32 v201, v165, v165
	v_mul_f32_e32 v202, v39, v39
	v_fmac_f32_e32 v202, v164, v164
	v_mul_f32_e32 v203, v40, v40
	v_fmac_f32_e32 v203, v163, v163
	ds_bpermute_b32 v204, v41, v145
	ds_bpermute_b32 v205, v41, v201
	ds_bpermute_b32 v206, v41, v202
	ds_bpermute_b32 v207, v41, v203
	s_waitcnt lgkmcnt(0)
	v_add_f32_e32 v145, v145, v204
	v_add_f32_e32 v201, v201, v205
	v_add_f32_e32 v202, v202, v206
	v_add_f32_e32 v203, v203, v207
	ds_bpermute_b32 v204, v42, v145
	ds_bpermute_b32 v205, v42, v201
	ds_bpermute_b32 v206, v42, v202
	ds_bpermute_b32 v207, v42, v203
	s_waitcnt lgkmcnt(0)
	v_add_f32_e32 v145, v145, v204
	v_add_f32_e32 v201, v201, v205
	v_add_f32_e32 v202, v202, v206
	v_add_f32_e32 v203, v203, v207
	ds_bpermute_b32 v204, v43, v145
	ds_bpermute_b32 v205, v43, v201
	ds_bpermute_b32 v206, v43, v202
	ds_bpermute_b32 v207, v43, v203
	s_waitcnt lgkmcnt(0)
	v_add_f32_e32 v145, v145, v204
	v_add_f32_e32 v201, v201, v205
	v_add_f32_e32 v202, v202, v206
	v_add_f32_e32 v203, v203, v207
	ds_bpermute_b32 v204, v44, v145
	ds_bpermute_b32 v205, v44, v201
	ds_bpermute_b32 v206, v44, v202
	ds_bpermute_b32 v207, v44, v203
	s_waitcnt lgkmcnt(0)
	v_add_f32_e32 v145, v145, v204
	v_add_f32_e32 v201, v201, v205
	v_add_f32_e32 v202, v202, v206
	v_add_f32_e32 v203, v203, v207
	s_and_saveexec_b64 s[84:85], s[8:9]
	s_cbranch_execz .LBB0_259
	ds_write_b32 v117, v145
	ds_write_b32 v117, v201 offset:4
	ds_write_b32 v117, v202 offset:8
	ds_write_b32 v117, v203 offset:12
	s_branch .LBB0_259

.LBB0_291:
	s_or_b64 exec, exec, s[20:21]
	ds_write_b128 v57, v[30:33] offset:32768
	ds_write_b128 v57, v[26:29] offset:32784
	ds_write_b128 v57, v[22:25] offset:32800
	ds_write_b128 v57, v[18:21] offset:32816
	s_waitcnt lgkmcnt(0)
	s_barrier
	s_lshl_b64 s[18:19], s[18:19], 5
	ds_read_b128 v[18:21], v63 offset:32768
	ds_read_b128 v[22:25], v64 offset:32768
	s_add_u32 s18, s18, s12
	s_addc_u32 s19, s19, s13
	s_or_b32 s18, s18, s25
	s_lshl_b64 s[18:19], s[18:19], 15
	v_lshl_add_u64 v[26:27], v[42:43], 0, s[18:19]
	s_movk_i32 s18, 0x2000
	s_waitcnt lgkmcnt(1)
	global_store_dwordx4 v[26:27], v[18:21], off
	s_waitcnt vmcnt(2)
	v_mov_b32_e32 v44, v67
	s_mov_b32 s33, s24
	v_add_co_u32_e32 v18, vcc, s18, v26
	s_nop 1
	v_addc_co_u32_e32 v19, vcc, 0, v27, vcc
	s_waitcnt lgkmcnt(0)
	global_store_dwordx4 v[18:19], v[22:25], off
	ds_read_b128 v[18:21], v65 offset:32768
	ds_read_b128 v[22:25], v66 offset:32768
	v_add_co_u32_e32 v28, vcc, 0x4000, v26
	s_nop 1
	v_addc_co_u32_e32 v29, vcc, 0, v27, vcc
	s_waitcnt lgkmcnt(1)
	global_store_dwordx4 v[28:29], v[18:21], off
	s_nop 1
	v_add_co_u32_e32 v18, vcc, 0x6000, v26
	s_nop 1
	v_addc_co_u32_e32 v19, vcc, 0, v27, vcc
	s_and_b64 vcc, exec, s[16:17]
	s_waitcnt lgkmcnt(0)
	global_store_dwordx4 v[18:19], v[22:25], off
	s_cbranch_vccnz .LBB0_303

.LBB0_300:
	v_add_u32_e32 v69, s18, v61
	ds_read_b32 v70, v69
	v_mov_b32_e32 v91, s19
	ds_read_b32 v71, v91
	ds_read_b32 v90, v91 offset:32
	s_add_i32 s19, s19, 8
	s_addk_i32 s18, 0x200
	s_cmpk_eq_i32 s18, 0x800
	s_waitcnt lgkmcnt(1)
	v_mul_f32_e32 v92, v70, v71
	ds_read_b128 v[70:73], v68
	ds_read_b128 v[74:77], v68 offset:16
	ds_read_b128 v[78:81], v68 offset:32
	ds_read_b128 v[82:85], v68 offset:48
	ds_read_b128 v[86:89], v68 offset:4096
	s_waitcnt lgkmcnt(4)
	v_pk_mul_f32 v[70:71], v[92:93], v[70:71] op_sel_hi:[0,1]
	v_pk_fma_f32 v[94:95], v[30:31], v[90:91], v[70:71] op_sel_hi:[1,0,1]
	s_waitcnt lgkmcnt(0)
	v_fma_f32 v93, v86, v94, 0
	v_fmac_f32_e32 v93, v87, v95
	v_pk_mul_f32 v[30:31], v[92:93], v[72:73] op_sel_hi:[0,1]
	v_pk_fma_f32 v[86:87], v[32:33], v[90:91], v[30:31] op_sel_hi:[1,0,1]
	ds_read_b128 v[30:33], v68 offset:4112
	v_fmac_f32_e32 v93, v88, v86
	v_fmac_f32_e32 v93, v89, v87
	v_pk_mul_f32 v[70:71], v[92:93], v[74:75] op_sel_hi:[0,1]
	v_pk_fma_f32 v[88:89], v[26:27], v[90:91], v[70:71] op_sel_hi:[1,0,1]
	s_waitcnt lgkmcnt(0)
	v_pk_mul_f32 v[26:27], v[30:31], v[88:89]
	s_nop 0
	v_add_f32_e32 v26, v26, v93
	v_add_f32_e32 v30, v27, v26
	v_pk_mul_f32 v[26:27], v[92:93], v[76:77] op_sel_hi:[0,1]
	v_pk_fma_f32 v[96:97], v[28:29], v[90:91], v[26:27] op_sel_hi:[1,0,1]
	s_nop 0
	v_pk_mul_f32 v[26:27], v[32:33], v[96:97]
	s_nop 0
	v_add_f32_e32 v26, v26, v30
	v_add_f32_e32 v32, v27, v26
	ds_read_b128 v[26:29], v68 offset:4128
	v_pk_mul_f32 v[30:31], v[92:93], v[78:79] op_sel_hi:[0,1]
	v_pk_fma_f32 v[78:79], v[22:23], v[90:91], v[30:31] op_sel_hi:[1,0,1]
	s_waitcnt lgkmcnt(0)
	v_pk_mul_f32 v[22:23], v[26:27], v[78:79]
	s_nop 0
	v_add_f32_e32 v22, v22, v32
	v_add_f32_e32 v26, v23, v22
	v_pk_mul_f32 v[22:23], v[92:93], v[80:81] op_sel_hi:[0,1]
	v_pk_fma_f32 v[80:81], v[24:25], v[90:91], v[22:23] op_sel_hi:[1,0,1]
	s_nop 0
	v_pk_mul_f32 v[22:23], v[28:29], v[80:81]
	s_nop 0
	v_add_f32_e32 v22, v22, v26
	v_add_f32_e32 v28, v23, v22
	ds_read_b128 v[22:25], v68 offset:4144
	v_pk_mul_f32 v[26:27], v[92:93], v[82:83] op_sel_hi:[0,1]
	v_pk_fma_f32 v[82:83], v[18:19], v[90:91], v[26:27] op_sel_hi:[1,0,1]
	s_waitcnt lgkmcnt(0)
	v_pk_mul_f32 v[18:19], v[22:23], v[82:83]
	s_nop 0
	v_add_f32_e32 v18, v18, v28
	v_add_f32_e32 v22, v19, v18
	v_pk_mul_f32 v[18:19], v[92:93], v[84:85] op_sel_hi:[0,1]
	v_pk_fma_f32 v[84:85], v[20:21], v[90:91], v[18:19] op_sel_hi:[1,0,1]
	s_nop 0
	v_pk_mul_f32 v[18:19], v[24:25], v[84:85]
	s_nop 0
	v_add_f32_e32 v18, v18, v22
	v_add_f32_e32 v18, v19, v18
	ds_write_b32 v37, v18
	ds_read_b32 v18, v69 offset:256
	ds_read_b32 v19, v91 offset:4
	ds_read_b32 v90, v91 offset:36
	s_waitcnt lgkmcnt(1)
	v_mul_f32_e32 v92, v18, v19
	ds_read_b128 v[18:21], v68 offset:512
	ds_read_b128 v[22:25], v68 offset:528
	ds_read_b128 v[70:73], v68 offset:544
	ds_read_b128 v[74:77], v68 offset:560
	ds_read_b128 v[26:29], v68 offset:4608
	s_waitcnt lgkmcnt(4)
	v_pk_mul_f32 v[18:19], v[92:93], v[18:19] op_sel_hi:[0,1]
	v_pk_fma_f32 v[30:31], v[94:95], v[90:91], v[18:19] op_sel_hi:[1,0,1]
	v_pk_mul_f32 v[18:19], v[92:93], v[20:21] op_sel_hi:[0,1]
	v_pk_fma_f32 v[32:33], v[86:87], v[90:91], v[18:19] op_sel_hi:[1,0,1]
	ds_read_b128 v[18:21], v68 offset:4624
	s_waitcnt lgkmcnt(1)
	v_fma_f32 v69, v26, v30, 0
	v_fmac_f32_e32 v69, v27, v31
	v_pk_mul_f32 v[22:23], v[92:93], v[22:23] op_sel_hi:[0,1]
	v_fmac_f32_e32 v69, v28, v32
	v_pk_fma_f32 v[26:27], v[88:89], v[90:91], v[22:23] op_sel_hi:[1,0,1]
	v_fmac_f32_e32 v69, v29, v33
	s_waitcnt lgkmcnt(0)
	v_pk_mul_f32 v[18:19], v[18:19], v[26:27]
	s_nop 0
	v_add_f32_e32 v18, v18, v69
	v_add_f32_e32 v22, v19, v18
	v_pk_mul_f32 v[18:19], v[92:93], v[24:25] op_sel_hi:[0,1]
	v_pk_fma_f32 v[28:29], v[96:97], v[90:91], v[18:19] op_sel_hi:[1,0,1]
	s_nop 0
	v_pk_mul_f32 v[18:19], v[20:21], v[28:29]
	s_nop 0
	v_add_f32_e32 v18, v18, v22
	v_add_f32_e32 v24, v19, v18
	ds_read_b128 v[18:21], v68 offset:4640
	v_pk_mul_f32 v[22:23], v[92:93], v[70:71] op_sel_hi:[0,1]
	v_pk_fma_f32 v[22:23], v[78:79], v[90:91], v[22:23] op_sel_hi:[1,0,1]
	s_waitcnt lgkmcnt(0)
	v_pk_mul_f32 v[18:19], v[18:19], v[22:23]
	s_nop 0
	v_add_f32_e32 v18, v18, v24
	v_add_f32_e32 v69, v19, v18
	v_pk_mul_f32 v[18:19], v[92:93], v[72:73] op_sel_hi:[0,1]
	v_pk_fma_f32 v[24:25], v[80:81], v[90:91], v[18:19] op_sel_hi:[1,0,1]
	ds_read_b128 v[70:73], v68 offset:4656
	v_pk_mul_f32 v[18:19], v[20:21], v[24:25]
	v_add_u32_e32 v68, 0x400, v68
	v_add_f32_e32 v18, v18, v69
	v_add_f32_e32 v69, v19, v18
	v_pk_mul_f32 v[18:19], v[92:93], v[74:75] op_sel_hi:[0,1]
	v_pk_fma_f32 v[18:19], v[82:83], v[90:91], v[18:19] op_sel_hi:[1,0,1]
	s_waitcnt lgkmcnt(0)
	v_pk_mul_f32 v[20:21], v[70:71], v[18:19]
	s_nop 0
	v_add_f32_e32 v20, v20, v69
	v_add_f32_e32 v69, v21, v20
	v_pk_mul_f32 v[20:21], v[92:93], v[76:77] op_sel_hi:[0,1]
	v_pk_fma_f32 v[20:21], v[84:85], v[90:91], v[20:21] op_sel_hi:[1,0,1]
	s_nop 0
	v_pk_mul_f32 v[70:71], v[72:73], v[20:21]
	s_nop 0
	v_add_f32_e32 v69, v70, v69
	v_add_f32_e32 v69, v71, v69
	ds_write_b32 v37, v69 offset:2048
	v_add_u32_e32 v37, 0x1000, v37
	s_cbranch_scc0 .LBB0_300
	s_waitcnt lgkmcnt(0)
	s_barrier
	v_add_u32_e32 v70, 64, v60
	s_waitcnt vmcnt(11)
	v_lshlrev_b32_e32 v37, 16, v44
	ds_read_b32 v44, v55 offset:8192
	ds_read2st64_b32 v[68:69], v70 offset0:40 offset1:41
	s_ashr_i32 s18, s33, 5
	s_ashr_i32 s19, s18, 31
	s_lshl_b32 s48, s25, 7
	s_waitcnt lgkmcnt(0)
	v_fma_f32 v44, v45, v44, v68
	v_add_f32_e32 v68, v44, v69
	ds_read2st64_b32 v[44:45], v70 offset0:42 offset1:43
	v_mul_f32_e32 v69, 0xbfb8aa3b, v37
	v_exp_f32_e32 v69, v69
	s_waitcnt lgkmcnt(0)
	v_add_f32_e32 v44, v68, v44
	v_add_f32_e32 v68, v44, v45
	ds_read2st64_b32 v[44:45], v70 offset0:44 offset1:45
	v_add_f32_e32 v69, 1.0, v69
	v_rcp_f32_e32 v69, v69
	s_waitcnt lgkmcnt(0)
	v_add_f32_e32 v44, v68, v44
	v_add_f32_e32 v68, v44, v45
	ds_read2st64_b32 v[44:45], v70 offset0:46 offset1:47
	v_mul_f32_e32 v37, v69, v37
	s_waitcnt lgkmcnt(0)
	v_add_f32_e32 v44, v68, v44
	v_add_f32_e32 v68, v44, v45
	v_lshl_add_u64 v[44:45], s[18:19], 3, v[40:41]
	v_mul_f32_e32 v70, v37, v68
	v_lshlrev_b64 v[68:69], 12, v[44:45]
	v_lshl_add_u64 v[68:69], s[74:75], 0, v[68:69]
	v_lshl_add_u64 v[68:69], v[68:69], 0, s[48:49]
	v_mov_b32_e32 v37, v1
	v_lshl_add_u64 v[68:69], v[68:69], 0, v[36:37]
	v_cvt_pk_bf16_f32 v71, v70, v70
	global_store_short v[68:69], v71, off
	v_and_b32_e32 v68, 64, v177
	v_add_u32_e32 v68, 64, v68
	v_xor_b32_e32 v69, 32, v177
	v_cmp_lt_i32_e32 vcc, v69, v68
	v_mul_f32_e32 v37, v70, v70
	s_nop 0
	v_cndmask_b32_e32 v69, v177, v69, vcc
	v_lshlrev_b32_e32 v69, 2, v69
	ds_bpermute_b32 v37, v69, v37
	v_xor_b32_e32 v69, 16, v177
	v_cmp_lt_i32_e32 vcc, v69, v68
	s_waitcnt lgkmcnt(0)
	v_fmac_f32_e32 v37, v70, v70
	v_cndmask_b32_e32 v69, v177, v69, vcc
	v_lshlrev_b32_e32 v69, 2, v69
	ds_bpermute_b32 v69, v69, v37
	s_waitcnt lgkmcnt(0)
	v_add_f32_e32 v37, v37, v69
	v_xor_b32_e32 v69, 8, v177
	v_cmp_lt_i32_e32 vcc, v69, v68
	s_nop 1
	v_cndmask_b32_e32 v69, v177, v69, vcc
	v_lshlrev_b32_e32 v69, 2, v69
	ds_bpermute_b32 v69, v69, v37
	s_waitcnt lgkmcnt(0)
	v_add_f32_e32 v37, v37, v69
	v_xor_b32_e32 v69, 4, v177
	v_cmp_lt_i32_e32 vcc, v69, v68
	s_nop 1
	v_cndmask_b32_e32 v69, v177, v69, vcc
	v_lshlrev_b32_e32 v69, 2, v69
	ds_bpermute_b32 v69, v69, v37
	s_waitcnt lgkmcnt(0)
	v_add_f32_e32 v37, v37, v69
	v_xor_b32_e32 v69, 2, v177
	v_cmp_lt_i32_e32 vcc, v69, v68
	s_nop 1
	v_cndmask_b32_e32 v69, v177, v69, vcc
	v_lshlrev_b32_e32 v69, 2, v69
	ds_bpermute_b32 v69, v69, v37
	s_waitcnt lgkmcnt(0)
	v_add_f32_e32 v37, v37, v69
	v_xor_b32_e32 v69, 1, v177
	v_cmp_lt_i32_e32 vcc, v69, v68
	s_nop 1
	v_cndmask_b32_e32 v68, v177, v69, vcc
	v_lshlrev_b32_e32 v68, 2, v68
	ds_bpermute_b32 v68, v68, v37
	s_and_saveexec_b64 s[20:21], s[8:9]
	s_cbranch_execz .LBB0_291
	s_waitcnt lgkmcnt(0)
	v_add_f32_e32 v37, v37, v68
	v_mul_f32_e32 v37, 0x4b800000, v37
	v_trunc_f32_e32 v37, v37
	v_mul_f32_e32 v68, 0x2f800000, v37
	v_floor_f32_e32 v69, v68
	s_lshr_b32 s26, s25, 3
	v_fmac_f32_e32 v37, 0xcf800000, v69
	s_mul_i32 s26, s26, 0x22000
	v_cvt_u32_f32_e32 v68, v37
	v_cvt_u32_f32_e32 v69, v69
	s_add_u32 s26, s4, s26
	s_addc_u32 s27, s5, 0
	v_lshl_add_u64 v[44:45], v[44:45], 3, s[26:27]
	global_atomic_add_x2 v[44:45], v[68:69], off
	s_branch .LBB0_291

.LBB0_596:
	v_readlane_b32 s6, v253, 12
	v_readlane_b32 s7, v253, 13
	v_readlane_b32 s0, v254, 35
	s_mov_b64 s[8:9], -1
	s_nop 2
	global_load_dword v0, v1, s[6:7] sc1
	v_readlane_b32 s6, v253, 14
	v_readlane_b32 s7, v253, 15
	s_waitcnt lgkmcnt(0)
	s_nop 3
	global_load_dword v2, v1, s[6:7] sc1
	v_readlane_b32 s6, v253, 16
	v_readlane_b32 s7, v253, 17
	s_nop 0
	s_nop 0
	s_nop 2
	global_load_dword v3, v1, s[6:7] sc1
	v_readlane_b32 s6, v253, 18
	v_readlane_b32 s7, v253, 19
	s_nop 0
	s_nop 0
	s_nop 2
	global_load_dword v4, v1, s[6:7] sc1
	v_readlane_b32 s6, v253, 20
	v_readlane_b32 s7, v253, 21
	s_nop 0
	s_nop 0
	s_nop 2
	global_load_dword v5, v1, s[6:7] sc1
	v_readlane_b32 s6, v253, 22
	v_readlane_b32 s7, v253, 23
	s_nop 0
	s_nop 0
	s_nop 2
	global_load_dword v6, v1, s[6:7] sc1
	v_readlane_b32 s6, v253, 24
	v_readlane_b32 s7, v253, 25
	s_nop 0
	s_nop 0
	s_nop 2
	global_load_dword v7, v1, s[6:7] sc1
	v_readlane_b32 s6, v253, 26
	v_readlane_b32 s7, v253, 27
	s_nop 0
	s_nop 0
	s_nop 2
	global_load_dword v8, v1, s[6:7] sc1
	v_readlane_b32 s6, v253, 28
	v_readlane_b32 s7, v253, 29
	s_nop 0
	s_nop 0
	s_nop 2
	global_load_dword v9, v1, s[6:7] sc1
	v_readlane_b32 s6, v253, 30
	v_readlane_b32 s7, v253, 31
	s_nop 0
	s_nop 0
	s_nop 2
	global_load_dword v10, v1, s[6:7] sc1
	v_readlane_b32 s6, v253, 32
	v_readlane_b32 s7, v253, 33
	s_nop 0
	s_nop 0
	s_nop 2
	global_load_dword v11, v1, s[6:7] sc1
	v_readlane_b32 s6, v253, 34
	v_readlane_b32 s7, v253, 35
	s_nop 0
	s_nop 0
	s_nop 2
	global_load_dword v12, v1, s[6:7] sc1
	v_readlane_b32 s6, v253, 36
	v_readlane_b32 s7, v253, 37
	s_nop 0
	s_nop 0
	s_nop 2
	global_load_dword v13, v1, s[6:7] sc1
	v_readlane_b32 s6, v253, 38
	v_readlane_b32 s7, v253, 39
	s_nop 0
	s_nop 0
	s_nop 2
	global_load_dword v14, v1, s[6:7] sc1
	v_readlane_b32 s6, v253, 40
	v_readlane_b32 s7, v253, 41
	s_nop 0
	s_nop 0
	s_nop 2
	global_load_dword v15, v1, s[6:7] sc1
	v_readlane_b32 s6, v253, 42
	v_readlane_b32 s7, v253, 43
	s_nop 0
	s_nop 0
	s_nop 2
	global_load_dword v16, v1, s[6:7] sc1
	s_mov_b64 s[6:7], -1
	s_nop 0
	s_nop 0
	s_waitcnt vmcnt(0)
	v_add_u32_e32 v17, v2, v0
	v_add_u32_e32 v17, v17, v3
	v_add_u32_e32 v17, v17, v4
	v_add_u32_e32 v17, v17, v5
	v_add_u32_e32 v17, v17, v6
	v_add_u32_e32 v17, v17, v7
	v_add_u32_e32 v17, v17, v8
	v_add_u32_e32 v17, v17, v9
	v_add_u32_e32 v17, v17, v10
	v_add_u32_e32 v17, v17, v11
	v_add_u32_e32 v17, v17, v12
	v_add_u32_e32 v17, v17, v13
	v_add_u32_e32 v17, v17, v14
	v_add_u32_e32 v17, v17, v15
	v_add_u32_e32 v17, v17, v16
	v_cmp_eq_u32_e32 vcc, s0, v17
	s_cbranch_vccnz .LBB0_595
	s_and_b32 s6, s5, 0xff
	s_cmp_eq_u32 s6, 0
	s_mov_b64 s[6:7], -1
	s_mov_b64 s[10:11], -1
	s_sleep 1
	s_cbranch_scc0 .LBB0_600
	v_readlane_b32 s6, v253, 10
	v_readlane_b32 s7, v253, 11
	s_nop 4
	global_load_dword v17, v1, s[6:7] sc1
	s_waitcnt vmcnt(0)
	v_cmp_eq_u32_e32 vcc, 0, v17
	s_cbranch_vccnz .LBB0_602
	s_mov_b64 s[10:11], 0
	s_mov_b64 s[6:7], -1

.LBB0_677:
	s_and_b64 vcc, exec, s[2:3]
	s_cbranch_vccz .LBB0_683
	v_readlane_b32 s0, v254, 59
	s_ashr_i32 s2, s0, 2
	s_and_b32 s4, s0, 3
	v_readlane_b32 s0, v254, 60
	v_mov_b32_e32 v50, v142
	v_readlane_b32 s1, v254, 61
	s_load_dwordx2 s[6:7], s[0:1], 0x78
	v_readlane_b32 s0, v255, 4
	s_waitcnt lgkmcnt(0)
	s_lshl_b32 s12, s0, 9
	s_lshl_b32 s3, s2, 7
	s_lshl_b32 s5, s4, 5
	s_ashr_i32 s13, s12, 31
	s_add_i32 s11, s89, 0x13c00
	s_or_b32 s8, s5, s3
	s_lshl_b64 s[12:13], s[12:13], 2
	s_add_u32 s3, s6, s12
	s_addc_u32 s5, s7, s13
	s_lshl_b32 s6, s4, 9
	v_lshlrev_b32_e32 v46, 4, v50
	s_add_u32 s6, s3, s6
	v_and_b32_e32 v51, 0x70, v46
	s_addc_u32 s7, s5, 0
	v_lshlrev_b32_e32 v53, 2, v51
	global_load_dwordx4 v[10:13], v53, s[6:7] offset:32
	global_load_dwordx4 v[14:17], v53, s[6:7] offset:48
	global_load_dwordx4 v[2:5], v53, s[6:7]
	global_load_dwordx4 v[6:9], v53, s[6:7] offset:16
	s_mul_i32 s10, s8, 0x10400
	s_mul_hi_i32 s9, s8, 0x10400
	s_add_u32 s3, s50, s10
	s_addc_u32 s5, s51, s9
	s_add_u32 s6, s3, 0x2ee9c000
	s_addc_u32 s7, s5, 0
	s_add_u32 s12, s3, 0x2eea4000
	s_addc_u32 s13, s5, 0
	s_add_u32 s14, s3, 0x2eea8000
	v_add_u32_e32 v48, 0x2000, v46
	s_addc_u32 s15, s5, 0
	v_ashrrev_i32_e32 v47, 31, v46
	v_ashrrev_i32_e32 v49, 31, v48
	s_waitcnt vmcnt(0)
	v_and_b32_e32 v153, 15, v50
	v_lshl_add_u64 v[42:43], s[6:7], 0, v[46:47]
	v_lshl_add_u64 v[38:39], s[14:15], 0, v[48:49]
	global_load_dwordx4 v[18:21], v[42:43], off
	v_lshl_add_u64 v[30:31], s[6:7], 0, v[48:49]
	global_load_dwordx4 v[38:41], v[38:39], off
	v_add_co_u32_e32 v42, vcc, s33, v42
	s_add_u32 s6, s3, 0x2eeac000
	v_or_b32_e32 v57, 32, v153
	v_or_b32_e32 v58, 48, v153
	v_or_b32_e32 v59, 64, v153
	v_lshl_add_u64 v[22:23], s[12:13], 0, v[46:47]
	v_lshl_add_u64 v[26:27], s[14:15], 0, v[46:47]
	v_lshl_add_u64 v[34:35], s[12:13], 0, v[48:49]
	v_addc_co_u32_e32 v43, vcc, 0, v43, vcc
	s_addc_u32 s7, s5, 0
	v_or_b32_e32 v60, 0x50, v153
	global_load_dwordx4 v[22:25], v[22:23], off
	v_or_b32_e32 v61, 0x60, v153
	global_load_dwordx4 v[26:29], v[26:27], off
	v_or_b32_e32 v62, 0x70, v153
	global_load_dwordx4 v[30:33], v[30:31], off
	v_ashrrev_i32_e32 v66, 2, v50
	global_load_dwordx4 v[34:37], v[34:35], off
	v_and_b32_e32 v68, 48, v66
	global_load_dwordx4 v[42:45], v[42:43], off
	v_or_b32_e32 v69, v68, v153
	s_movk_i32 s12, 0x110
	v_ashrrev_i32_e32 v54, 3, v50
	s_movk_i32 s13, 0x90
	v_mul_lo_u32 v64, v54, s13
	v_and_b32_e32 v118, -16, v66
	s_ashr_i32 s3, s2, 31
	v_ashrrev_i32_e32 v55, 31, v54
	v_lshrrev_b32_e32 v52, 4, v50
	s_movk_i32 s0, 0x210
	v_add_u32_e32 v53, s89, v53
	v_mul_lo_u32 v52, v52, s12
	s_mov_b32 s5, 32
	v_mov_b32_e32 v133, s9
	v_readlane_b32 s1, v255, 5
	s_waitcnt vmcnt(10)
	v_mov_b32_e32 v113, v12
	v_or_b32_e32 v12, 16, v153
	s_waitcnt vmcnt(8)
	v_mov_b32_e32 v103, v2
	v_mov_b32_e32 v105, v4
	s_waitcnt vmcnt(7)
	v_mov_b32_e32 v107, v6
	v_mov_b32_e32 v109, v8
	v_mov_b32_e32 v115, v14
	v_lshlrev_b32_e32 v8, 2, v153
	v_lshlrev_b32_e32 v2, 2, v12
	v_lshlrev_b32_e32 v4, 2, v57
	v_lshlrev_b32_e32 v6, 2, v58
	v_lshlrev_b32_e32 v14, 2, v59
	v_mov_b32_e32 v117, v16
	global_load_dword v119, v8, s[6:7]
	global_load_dword v0, v8, s[6:7] offset:512
	global_load_dword v154, v2, s[6:7]
	s_nop 0
	global_load_dword v2, v2, s[6:7] offset:512
	s_nop 0
	global_load_dword v155, v4, s[6:7]
	s_nop 0
	global_load_dword v4, v4, s[6:7] offset:512
	s_nop 0
	global_load_dword v156, v6, s[6:7]
	s_nop 0
	global_load_dword v6, v6, s[6:7] offset:512
	s_nop 0
	global_load_dword v157, v14, s[6:7]
	global_load_dword v16, v14, s[6:7] offset:512
	v_lshlrev_b32_e32 v14, 2, v60
	global_load_dword v158, v14, s[6:7]
	global_load_dword v78, v14, s[6:7] offset:512
	v_lshlrev_b32_e32 v14, 2, v61
	global_load_dword v170, v14, s[6:7]
	global_load_dword v79, v14, s[6:7] offset:512
	v_lshlrev_b32_e32 v14, 2, v62
	global_load_dword v194, v14, s[6:7]
	global_load_dword v80, v14, s[6:7] offset:512
	v_mov_b32_e32 v111, v10
	v_bfe_u32 v10, v50, 4, 2
	v_lshlrev_b32_e32 v70, 4, v10
	v_lshlrev_b32_e32 v159, 2, v10
	v_add_u32_e32 v10, s89, v70
	s_add_i32 s6, s89, 0x11800
	v_mad_u32_u24 v160, v69, s12, v10
	v_mul_u32_u24_e32 v69, 0x90, v69
	v_and_b32_e32 v14, 0xf0, v46
	v_add3_u32 v161, s6, v69, v70
	v_bfi_b32 v69, -16, v66, v50
	v_add_u32_e32 v63, s89, v14
	v_add_u32_e32 v14, s89, v51
	v_add_u32_e32 v65, s6, v64
	v_mad_u64_u32 v[120:121], s[6:7], v69, s13, v[10:11]
	v_add_u32_e32 v121, v14, v64
	v_add_u32_e32 v64, 0x200, v50
	v_or_b32_e32 v67, v159, v118
	v_lshrrev_b32_e32 v71, 4, v64
	v_lshrrev_b32_e32 v64, 3, v64
	v_mad_u64_u32 v[122:123], s[6:7], v64, s13, v[14:15]
	v_mul_lo_u32 v14, v67, s12
	v_add_u32_e32 v64, s11, v14
	v_lshlrev_b32_e32 v12, 1, v12
	v_add_u32_e32 v162, v64, v12
	v_add3_u32 v163, s11, v12, v14
	v_lshlrev_b32_e32 v12, 1, v57
	v_add_u32_e32 v164, v64, v12
	v_add3_u32 v165, s11, v12, v14
	v_lshlrev_b32_e32 v12, 1, v58
	v_add_u32_e32 v166, v64, v12
	v_add3_u32 v167, s11, v12, v14
	v_lshlrev_b32_e32 v12, 1, v59
	v_add_u32_e32 v168, v64, v12
	v_add3_u32 v169, s11, v12, v14
	v_lshlrev_b32_e32 v12, 1, v60
	v_add_u32_e32 v171, v64, v12
	v_add3_u32 v188, s11, v12, v14
	v_lshlrev_b32_e32 v12, 1, v61
	v_add_u32_e32 v189, v64, v12
	v_add3_u32 v190, s11, v12, v14
	v_lshlrev_b32_e32 v12, 1, v62
	v_add3_u32 v192, s11, v12, v14
	s_movk_i32 s6, 0xffc0
	v_or_b32_e32 v14, 48, v69
	v_or_b32_e32 v68, v68, v159
	v_add_u32_e32 v191, v64, v12
	v_and_or_b32 v12, v66, s6, v153
	v_mad_u64_u32 v[130:131], s[6:7], v14, s13, v[10:11]
	v_add_u32_e32 v56, s11, v70
	v_mad_u64_u32 v[128:129], s[6:7], v12, s13, v[10:11]
	v_mad_u32_u24 v131, v153, s13, v10
	v_mul_u32_u24_e32 v10, 0x84, v68
	v_or_b32_e32 v132, s10, v8
	v_mov_b32_e32 v8, 0x10400
	v_mad_u64_u32 v[124:125], s[6:7], v12, s12, v[56:57]
	v_mad_u64_u32 v[126:127], s[6:7], v14, s12, v[56:57]
	v_lshlrev_b32_e32 v12, 2, v12
	v_lshlrev_b32_e32 v10, 2, v10
	v_mad_i64_i32 v[134:135], s[6:7], s8, v8, v[46:47]
	v_mad_i64_i32 v[136:137], s[6:7], s8, v8, v[48:49]
	v_add3_u32 v202, s89, v12, v10
	v_lshlrev_b32_e32 v12, 2, v14
	s_lshl_b64 s[6:7], s[2:3], 22
	v_lshlrev_b64 v[46:47], 11, v[54:55]
	v_add3_u32 v203, s89, v12, v10
	v_lshl_add_u64 v[138:139], s[6:7], 0, v[46:47]
	v_lshlrev_b32_e32 v8, 5, v50
	v_mad_i64_i32 v[46:47], s[6:7], v54, s82, 0
	v_mov_b32_e32 v10, 0xc00000
	v_mul_lo_u32 v70, v54, s0
	v_mul_lo_u32 v71, v71, s12
	s_lshl_b32 s8, s4, 8
	v_and_b32_e32 v8, 0xe0, v8
	v_mad_i64_i32 v[140:141], s[6:7], s2, v10, v[46:47]
	v_mov_b32_e32 v46, 0
	v_lshl_add_u32 v123, v153, 1, v64
	v_add_u32_e32 v125, 0x1100, v124
	v_add_u32_e32 v193, 0x2200, v124
	v_add_u32_e32 v127, 0x900, v128
	v_add_u32_e32 v129, 0x1200, v128
	v_add_u32_e32 v195, 0x900, v131
	v_add_u32_e32 v196, 0x1200, v131
	v_add_u32_e32 v197, 0x1b00, v131
	v_add_u32_e32 v198, 0x2400, v131
	v_add_u32_e32 v199, 0x2d00, v131
	v_add_u32_e32 v200, 0x3600, v131
	v_add_u32_e32 v201, 0x3f00, v131
	v_or3_b32 v138, v138, s8, v8
	v_or3_b32 v140, v140, s8, v8
	v_add_u32_e32 v204, v63, v52
	v_add_u32_e32 v205, v63, v71
	v_add_u32_e32 v206, v65, v51
	v_add_u32_e32 v207, v53, v70
	v_mov_b32_e32 v47, v46
	v_mov_b32_e32 v48, v46
	v_mov_b32_e32 v49, v46
	v_mov_b32_e32 v74, v46
	v_mov_b32_e32 v75, v46
	v_mov_b32_e32 v76, v46
	v_mov_b32_e32 v77, v46
	v_mov_b32_e32 v66, v46
	v_mov_b32_e32 v67, v46
	v_mov_b32_e32 v68, v46
	v_mov_b32_e32 v69, v46
	v_mov_b32_e32 v58, v46
	v_mov_b32_e32 v59, v46
	v_mov_b32_e32 v60, v46
	v_mov_b32_e32 v61, v46
	v_mov_b32_e32 v54, v46
	v_mov_b32_e32 v55, v46
	v_mov_b32_e32 v56, v46
	v_mov_b32_e32 v57, v46
	v_mov_b32_e32 v50, v46
	v_mov_b32_e32 v51, v46
	v_mov_b32_e32 v52, v46
	v_mov_b32_e32 v53, v46
	v_mov_b32_e32 v70, v46
	v_mov_b32_e32 v71, v46
	v_mov_b32_e32 v72, v46
	v_mov_b32_e32 v73, v46
	v_mov_b32_e32 v62, v46
	v_mov_b32_e32 v63, v46
	v_mov_b32_e32 v64, v46
	v_mov_b32_e32 v65, v46
	s_waitcnt vmcnt(14)
	v_mov_b32_e32 v208, v0
	s_waitcnt vmcnt(12)
	v_mov_b32_e32 v209, v2
	s_waitcnt vmcnt(10)
	v_mov_b32_e32 v210, v4
	s_waitcnt vmcnt(8)
	v_mov_b32_e32 v211, v6
	s_waitcnt vmcnt(6)
	v_mov_b32_e32 v212, v16
	s_waitcnt vmcnt(4)
	v_mov_b32_e32 v213, v78
	s_waitcnt vmcnt(2)
	v_mov_b32_e32 v214, v79
	s_waitcnt vmcnt(0)
	v_mov_b32_e32 v215, v80
	s_mov_b64 s[8:9], 0x10400
	v_and_b32_e32 v251, 1, v177
	v_cmp_eq_u32_e64 s[98:99], 1, v251
	v_mov_b32_e32 v239, 0x10e
	v_mov_b32_e32 v240, 0x5040100
	v_mov_b32_e32 v241, 0x3020706
	v_cndmask_b32_e64 v239, 0, v239, s[98:99]
	v_cndmask_b32_e64 v238, v240, v241, s[98:99]
	v_add_u32_e32 v230, v123, v239
	v_add_u32_e32 v231, v162, v239
	v_add_u32_e32 v232, v164, v239
	v_add_u32_e32 v233, v166, v239
	v_add_u32_e32 v234, v168, v239
	v_add_u32_e32 v235, v171, v239
	v_add_u32_e32 v236, v189, v239
	v_add_u32_e32 v237, v191, v239
	s_branch .LBB0_680

.LBB0_680:
	v_mul_f32_e32 v8, 0x3fb8aa3b, v119
	v_exp_f32_e32 v8, v8
	s_waitcnt lgkmcnt(0)
	s_barrier
	ds_write_b128 v204, v[18:21]
	ds_write_b128 v121, v[22:25] offset:34816
	ds_write_b128 v121, v[26:29] offset:53248
	ds_write_b128 v205, v[30:33]
	ds_write_b128 v122, v[34:37] offset:34816
	ds_write_b128 v122, v[38:41] offset:53248
	ds_write_b128 v206, v[42:45]
	v_mul_f32_e32 v239, v8, v46
	v_mul_f32_e32 v240, v8, v47
	v_cvt_pk_bf16_f32 v241, v239, v240
	v_mul_f32_e32 v243, v8, v48
	v_mul_f32_e32 v244, v8, v49
	v_cvt_pk_bf16_f32 v245, v243, v244
	v_mov_b32_dpp v242, v241 quad_perm:[1,0,3,2] row_mask:0xf bank_mask:0xf
	v_perm_b32 v239, v242, v241, v238
	ds_write_b32 v230, v239
	v_mul_f32_e32 v10, 0x3fb8aa3b, v154
	v_exp_f32_e32 v10, v10
	s_nop 0
	v_mul_f32_e32 v247, v10, v74
	v_mul_f32_e32 v248, v10, v75
	v_cvt_pk_bf16_f32 v249, v247, v248
	v_mov_b32_dpp v246, v245 quad_perm:[1,0,3,2] row_mask:0xf bank_mask:0xf
	v_perm_b32 v243, v246, v245, v238
	ds_write_b32 v230, v243 offset:544
	v_mul_f32_e32 v239, v10, v76
	v_mul_f32_e32 v240, v10, v77
	v_cvt_pk_bf16_f32 v241, v239, v240
	v_mov_b32_dpp v250, v249 quad_perm:[1,0,3,2] row_mask:0xf bank_mask:0xf
	v_perm_b32 v247, v250, v249, v238
	ds_write_b32 v231, v247
	v_mul_f32_e32 v8, 0x3fb8aa3b, v155
	v_exp_f32_e32 v8, v8
	s_nop 0
	v_mul_f32_e32 v243, v8, v66
	v_mul_f32_e32 v244, v8, v67
	v_cvt_pk_bf16_f32 v245, v243, v244
	v_mov_b32_dpp v242, v241 quad_perm:[1,0,3,2] row_mask:0xf bank_mask:0xf
	v_perm_b32 v239, v242, v241, v238
	ds_write_b32 v231, v239 offset:544
	v_mul_f32_e32 v247, v8, v68
	v_mul_f32_e32 v248, v8, v69
	v_cvt_pk_bf16_f32 v249, v247, v248
	v_mov_b32_dpp v246, v245 quad_perm:[1,0,3,2] row_mask:0xf bank_mask:0xf
	v_perm_b32 v243, v246, v245, v238
	ds_write_b32 v232, v243
	v_mul_f32_e32 v10, 0x3fb8aa3b, v156
	v_exp_f32_e32 v10, v10
	s_nop 0
	v_mul_f32_e32 v239, v10, v58
	v_mul_f32_e32 v240, v10, v59
	v_cvt_pk_bf16_f32 v241, v239, v240
	v_mov_b32_dpp v250, v249 quad_perm:[1,0,3,2] row_mask:0xf bank_mask:0xf
	v_perm_b32 v247, v250, v249, v238
	ds_write_b32 v232, v247 offset:544
	v_mul_f32_e32 v243, v10, v60
	v_mul_f32_e32 v244, v10, v61
	v_cvt_pk_bf16_f32 v245, v243, v244
	v_mov_b32_dpp v242, v241 quad_perm:[1,0,3,2] row_mask:0xf bank_mask:0xf
	v_perm_b32 v239, v242, v241, v238
	ds_write_b32 v233, v239
	v_mul_f32_e32 v8, 0x3fb8aa3b, v157
	v_exp_f32_e32 v8, v8
	s_nop 0
	v_mul_f32_e32 v247, v8, v54
	v_mul_f32_e32 v248, v8, v55
	v_cvt_pk_bf16_f32 v249, v247, v248
	v_mov_b32_dpp v246, v245 quad_perm:[1,0,3,2] row_mask:0xf bank_mask:0xf
	v_perm_b32 v243, v246, v245, v238
	ds_write_b32 v233, v243 offset:544
	v_mul_f32_e32 v239, v8, v56
	v_mul_f32_e32 v240, v8, v57
	v_cvt_pk_bf16_f32 v241, v239, v240
	v_mov_b32_dpp v250, v249 quad_perm:[1,0,3,2] row_mask:0xf bank_mask:0xf
	v_perm_b32 v247, v250, v249, v238
	ds_write_b32 v234, v247
	v_mul_f32_e32 v10, 0x3fb8aa3b, v158
	v_exp_f32_e32 v10, v10
	s_nop 0
	v_mul_f32_e32 v243, v10, v50
	v_mul_f32_e32 v244, v10, v51
	v_cvt_pk_bf16_f32 v245, v243, v244
	v_mov_b32_dpp v242, v241 quad_perm:[1,0,3,2] row_mask:0xf bank_mask:0xf
	v_perm_b32 v239, v242, v241, v238
	ds_write_b32 v234, v239 offset:544
	v_mul_f32_e32 v247, v10, v52
	v_mul_f32_e32 v248, v10, v53
	v_cvt_pk_bf16_f32 v249, v247, v248
	v_mov_b32_dpp v246, v245 quad_perm:[1,0,3,2] row_mask:0xf bank_mask:0xf
	v_perm_b32 v243, v246, v245, v238
	ds_write_b32 v235, v243
	v_mul_f32_e32 v8, 0x3fb8aa3b, v170
	v_exp_f32_e32 v8, v8
	s_nop 0
	v_mul_f32_e32 v239, v8, v70
	v_mul_f32_e32 v240, v8, v71
	v_cvt_pk_bf16_f32 v241, v239, v240
	v_mov_b32_dpp v250, v249 quad_perm:[1,0,3,2] row_mask:0xf bank_mask:0xf
	v_perm_b32 v247, v250, v249, v238
	ds_write_b32 v235, v247 offset:544
	v_mul_f32_e32 v243, v8, v72
	v_mul_f32_e32 v244, v8, v73
	v_cvt_pk_bf16_f32 v245, v243, v244
	v_mov_b32_dpp v242, v241 quad_perm:[1,0,3,2] row_mask:0xf bank_mask:0xf
	v_perm_b32 v239, v242, v241, v238
	ds_write_b32 v236, v239
	v_mul_f32_e32 v10, 0x3fb8aa3b, v194
	v_exp_f32_e32 v10, v10
	s_nop 0
	v_mul_f32_e32 v247, v10, v62
	v_mul_f32_e32 v248, v10, v63
	v_cvt_pk_bf16_f32 v249, v247, v248
	v_mov_b32_dpp v246, v245 quad_perm:[1,0,3,2] row_mask:0xf bank_mask:0xf
	v_perm_b32 v243, v246, v245, v238
	ds_write_b32 v236, v243 offset:544
	v_mul_f32_e32 v239, v10, v64
	v_mul_f32_e32 v240, v10, v65
	v_cvt_pk_bf16_f32 v241, v239, v240
	v_mov_b32_dpp v250, v249 quad_perm:[1,0,3,2] row_mask:0xf bank_mask:0xf
	v_perm_b32 v247, v250, v249, v238
	ds_write_b32 v237, v247
	s_nop 1
	v_mov_b32_dpp v242, v241 quad_perm:[1,0,3,2] row_mask:0xf bank_mask:0xf
	v_perm_b32 v239, v242, v241, v238
	ds_write_b32 v237, v239 offset:544
	s_cmp_eq_u32 s5, 1
	s_cbranch_scc1 .LBB0_679
	v_lshl_add_u64 v[42:43], s[50:51], 0, v[134:135]
	v_add_co_u32_e32 v18, vcc, 0x2eeac000, v42
	v_lshl_add_u64 v[34:35], s[50:51], 0, v[136:137]
	s_nop 0
	v_addc_co_u32_e32 v19, vcc, 0, v43, vcc
	v_add_co_u32_e32 v22, vcc, 0x2eeb4000, v42
	s_mov_b32 s6, 0x2eeac000
	s_nop 0
	v_addc_co_u32_e32 v23, vcc, 0, v43, vcc
	v_add_co_u32_e32 v26, vcc, 0x2eeb8000, v42
	v_lshl_add_u64 v[44:45], s[50:51], 0, v[132:133]
	s_nop 0
	v_addc_co_u32_e32 v27, vcc, 0, v43, vcc
	v_add_co_u32_e32 v30, vcc, s6, v34
	global_load_dwordx4 v[18:21], v[18:19], off offset:1024
	s_nop 0
	global_load_dwordx4 v[22:25], v[22:23], off offset:1024
	v_addc_co_u32_e32 v31, vcc, 0, v35, vcc
	v_add_co_u32_e32 v36, vcc, 0x2eeb4000, v34
	global_load_dwordx4 v[26:29], v[26:27], off offset:1024
	s_nop 0
	global_load_dwordx4 v[30:33], v[30:31], off offset:1024
	v_addc_co_u32_e32 v37, vcc, 0, v35, vcc
	v_add_co_u32_e32 v38, vcc, 0x2eeb8000, v34
	s_nop 1
	v_addc_co_u32_e32 v39, vcc, 0, v35, vcc
	v_add_co_u32_e32 v42, vcc, 0x2eeb0000, v42
	global_load_dwordx4 v[34:37], v[36:37], off offset:1024
	s_nop 0
	global_load_dwordx4 v[38:41], v[38:39], off offset:1024
	v_addc_co_u32_e32 v43, vcc, 0, v43, vcc
	v_add_co_u32_e32 v82, vcc, 0x2eebc000, v44
	s_nop 1
	v_addc_co_u32_e32 v83, vcc, 0, v45, vcc
	global_load_dwordx4 v[42:45], v[42:43], off offset:1024
	s_nop 0
	global_load_dword v119, v[82:83], off offset:1024
	global_load_dword v154, v[82:83], off offset:1088
	global_load_dword v155, v[82:83], off offset:1152
	global_load_dword v208, v[82:83], off offset:1536
	global_load_dword v209, v[82:83], off offset:1600
	global_load_dword v210, v[82:83], off offset:1664
	global_load_dword v156, v[82:83], off offset:1216
	global_load_dword v157, v[82:83], off offset:1280
	global_load_dword v158, v[82:83], off offset:1344
	global_load_dword v170, v[82:83], off offset:1408
	global_load_dword v194, v[82:83], off offset:1472
	global_load_dword v211, v[82:83], off offset:1728
	global_load_dword v212, v[82:83], off offset:1792
	global_load_dword v213, v[82:83], off offset:1856
	global_load_dword v214, v[82:83], off offset:1920
	global_load_dword v215, v[82:83], off offset:1984
	s_branch .LBB0_679

.LBB0_820:
	v_mov_b64_e32 v[16:17], v[50:51]
.LBB0_821:
	ds_read2_b32 v[20:21], v32 offset1:65
	v_ashrrev_i32_e32 v19, 31, v18
	v_lshlrev_b64 v[18:19], 11, v[18:19]
	v_lshl_add_u64 v[14:15], v[14:15], 0, v[18:19]
	s_waitcnt lgkmcnt(0)
	v_mul_f32_e32 v0, v16, v20
	v_mul_f32_e32 v13, v17, v21
	v_cvt_pk_bf16_f32 v0, v0, v13
	global_store_dword v[14:15], v0, off

.LBB0_829:
	ds_read2_b32 v[36:37], v26 offset1:65
	v_ashrrev_i32_e32 v19, 31, v18
	v_lshlrev_b64 v[18:19], 11, v[18:19]
	v_lshl_add_u64 v[18:19], v[14:15], 0, v[18:19]
	s_waitcnt vmcnt(0) lgkmcnt(0)
	v_mov_b64_e32 v[50:51], v[20:21]
	v_mul_f32_e32 v0, v20, v36
	v_mul_f32_e32 v13, v21, v37
	v_cvt_pk_bf16_f32 v0, v0, v13
	global_store_dword v[18:19], v0, off
.LBB0_830:
	s_or_b64 exec, exec, s[12:13]
	v_add_u32_e32 v18, s4, v27
	v_cmp_gt_i32_e32 vcc, s5, v18
	s_and_saveexec_b64 s[12:13], vcc
	s_cbranch_execz .LBB0_835
	s_andn2_b64 vcc, exec, s[8:9]
	s_cbranch_vccnz .LBB0_833
	v_mov_b64_e32 v[20:21], v[50:51]
	s_branch .LBB0_834

.LBB0_834:
	ds_read2_b32 v[36:37], v28 offset1:65
	v_ashrrev_i32_e32 v19, 31, v18
	v_lshlrev_b64 v[18:19], 11, v[18:19]
	v_lshl_add_u64 v[18:19], v[14:15], 0, v[18:19]
	s_waitcnt lgkmcnt(0)
	v_mul_f32_e32 v0, v20, v36
	v_mul_f32_e32 v13, v21, v37
	v_cvt_pk_bf16_f32 v0, v0, v13
	global_store_dword v[18:19], v0, off
.LBB0_835:
	s_or_b64 exec, exec, s[12:13]
	v_add_u32_e32 v18, s4, v29
	v_cmp_gt_i32_e32 vcc, s5, v18
	s_and_saveexec_b64 s[12:13], vcc
	s_cbranch_execz .LBB0_840
	s_andn2_b64 vcc, exec, s[8:9]
	s_cbranch_vccnz .LBB0_838
	v_mov_b64_e32 v[20:21], v[50:51]
	s_branch .LBB0_839

.LBB0_839:
	ds_read2_b32 v[36:37], v30 offset1:65
	v_ashrrev_i32_e32 v19, 31, v18
	v_lshlrev_b64 v[18:19], 11, v[18:19]
	v_lshl_add_u64 v[18:19], v[14:15], 0, v[18:19]
	s_waitcnt lgkmcnt(0)
	v_mul_f32_e32 v0, v20, v36
	v_mul_f32_e32 v13, v21, v37
	v_cvt_pk_bf16_f32 v0, v0, v13
	global_store_dword v[18:19], v0, off

.LBB0_862:
	v_mov_b64_e32 v[14:15], v[50:51]
.LBB0_863:
	ds_read2_b32 v[18:19], v31 offset1:65
	v_ashrrev_i32_e32 v17, 31, v16
	v_lshlrev_b64 v[16:17], 11, v[16:17]
	v_lshl_add_u64 v[12:13], v[12:13], 0, v[16:17]
	s_waitcnt lgkmcnt(0)
	v_mul_f32_e32 v14, v14, v18
	v_mul_f32_e32 v15, v15, v19
	v_cvt_pk_bf16_f32 v14, v14, v15
	global_store_dword v[12:13], v14, off

.LBB0_875:
	ds_read2_b32 v[32:33], v25 offset1:65
	v_ashrrev_i32_e32 v17, 31, v16
	v_lshlrev_b64 v[16:17], 11, v[16:17]
	v_lshl_add_u64 v[16:17], v[12:13], 0, v[16:17]
	s_waitcnt vmcnt(0) lgkmcnt(0)
	v_mov_b64_e32 v[50:51], v[18:19]
	v_mul_f32_e32 v18, v18, v32
	v_mul_f32_e32 v19, v19, v33
	v_cvt_pk_bf16_f32 v18, v18, v19
	global_store_dword v[16:17], v18, off
.LBB0_876:
	s_or_b64 exec, exec, s[12:13]
	v_add_u32_e32 v16, s14, v26
	s_movk_i32 s12, 0x1420
	v_cmp_gt_i32_e32 vcc, s12, v16
	s_and_saveexec_b64 s[12:13], vcc
	s_cbranch_execz .LBB0_881
	s_andn2_b64 vcc, exec, s[8:9]
	s_cbranch_vccnz .LBB0_879
	v_mov_b64_e32 v[18:19], v[50:51]
	s_branch .LBB0_880

.LBB0_880:
	ds_read2_b32 v[32:33], v27 offset1:65
	v_ashrrev_i32_e32 v17, 31, v16
	v_lshlrev_b64 v[16:17], 11, v[16:17]
	v_lshl_add_u64 v[16:17], v[12:13], 0, v[16:17]
	s_waitcnt lgkmcnt(0)
	v_mul_f32_e32 v18, v18, v32
	v_mul_f32_e32 v19, v19, v33
	v_cvt_pk_bf16_f32 v18, v18, v19
	global_store_dword v[16:17], v18, off
.LBB0_881:
	s_or_b64 exec, exec, s[12:13]
	v_add_u32_e32 v16, s14, v28
	s_movk_i32 s12, 0x1420
	v_cmp_gt_i32_e32 vcc, s12, v16
	s_and_saveexec_b64 s[12:13], vcc
	s_cbranch_execz .LBB0_886
	s_andn2_b64 vcc, exec, s[8:9]
	s_cbranch_vccnz .LBB0_884
	v_mov_b64_e32 v[18:19], v[50:51]
	s_branch .LBB0_885

.LBB0_885:
	ds_read2_b32 v[32:33], v29 offset1:65
	v_ashrrev_i32_e32 v17, 31, v16
	v_lshlrev_b64 v[16:17], 11, v[16:17]
	v_lshl_add_u64 v[16:17], v[12:13], 0, v[16:17]
	s_waitcnt lgkmcnt(0)
	v_mul_f32_e32 v18, v18, v32
	v_mul_f32_e32 v19, v19, v33
	v_cvt_pk_bf16_f32 v18, v18, v19
	global_store_dword v[16:17], v18, off

.LBB0_892:
	v_ashrrev_i32_e32 v13, 31, v0
	v_lshrrev_b32_e32 v13, 22, v13
	v_add_u32_e32 v13, v0, v13
	v_ashrrev_i32_e32 v31, 10, v13
	ds_read2_b32 v[18:19], v30 offset1:65
	v_mul_i32_i24_e32 v31, 0x400, v31
	v_and_b32_e32 v13, 0xfffffc00, v13
	v_sub_u32_e32 v0, v0, v31
	v_add_u32_e32 v32, v13, v0
	v_ashrrev_i32_e32 v33, 31, v32
	s_waitcnt lgkmcnt(0)
	v_mul_f32_e32 v0, v16, v18
	v_mul_f32_e32 v13, v17, v19
	v_lshlrev_b64 v[16:17], 12, v[32:33]
	v_lshl_add_u64 v[14:15], v[14:15], 0, v[16:17]
	v_cvt_pk_bf16_f32 v0, v0, v13
	global_store_dword v[14:15], v0, off

.LBB0_900:
	v_ashrrev_i32_e32 v13, 31, v0
	v_lshrrev_b32_e32 v13, 22, v13
	v_add_u32_e32 v13, v0, v13
	v_ashrrev_i32_e32 v31, 10, v13
	ds_read2_b32 v[32:33], v24 offset1:65
	v_mul_i32_i24_e32 v31, 0x400, v31
	v_and_b32_e32 v13, 0xfffffc00, v13
	v_sub_u32_e32 v0, v0, v31
	v_add_u32_e32 v36, v13, v0
	v_ashrrev_i32_e32 v37, 31, v36
	s_waitcnt vmcnt(0) lgkmcnt(0)
	v_mov_b64_e32 v[50:51], v[18:19]
	v_mul_f32_e32 v0, v18, v32
	v_mul_f32_e32 v13, v19, v33
	v_lshlrev_b64 v[18:19], 12, v[36:37]
	v_lshl_add_u64 v[18:19], v[14:15], 0, v[18:19]
	v_cvt_pk_bf16_f32 v0, v0, v13
	global_store_dword v[18:19], v0, off
.LBB0_901:
	s_or_b64 exec, exec, s[12:13]
	v_add_u32_e32 v0, s14, v25
	v_cmp_gt_i32_e32 vcc, s83, v0
	s_and_saveexec_b64 s[12:13], vcc
	s_cbranch_execz .LBB0_906
	s_andn2_b64 vcc, exec, s[2:3]
	s_cbranch_vccnz .LBB0_904
	v_mov_b64_e32 v[18:19], v[50:51]
	s_branch .LBB0_905

.LBB0_905:
	v_ashrrev_i32_e32 v13, 31, v0
	v_lshrrev_b32_e32 v13, 22, v13
	v_add_u32_e32 v13, v0, v13
	v_ashrrev_i32_e32 v31, 10, v13
	ds_read2_b32 v[32:33], v26 offset1:65
	v_mul_i32_i24_e32 v31, 0x400, v31
	v_and_b32_e32 v13, 0xfffffc00, v13
	v_sub_u32_e32 v0, v0, v31
	v_add_u32_e32 v36, v13, v0
	v_ashrrev_i32_e32 v37, 31, v36
	s_waitcnt lgkmcnt(0)
	v_mul_f32_e32 v0, v18, v32
	v_mul_f32_e32 v13, v19, v33
	v_lshlrev_b64 v[18:19], 12, v[36:37]
	v_lshl_add_u64 v[18:19], v[14:15], 0, v[18:19]
	v_cvt_pk_bf16_f32 v0, v0, v13
	global_store_dword v[18:19], v0, off
.LBB0_906:
	s_or_b64 exec, exec, s[12:13]
	v_add_u32_e32 v0, s14, v27
	v_cmp_gt_i32_e32 vcc, s83, v0
	s_and_saveexec_b64 s[12:13], vcc
	s_cbranch_execz .LBB0_911
	s_andn2_b64 vcc, exec, s[2:3]
	s_cbranch_vccnz .LBB0_909
	v_mov_b64_e32 v[18:19], v[50:51]
	s_branch .LBB0_910

.LBB0_910:
	v_ashrrev_i32_e32 v13, 31, v0
	v_lshrrev_b32_e32 v13, 22, v13
	v_add_u32_e32 v13, v0, v13
	v_ashrrev_i32_e32 v31, 10, v13
	ds_read2_b32 v[32:33], v28 offset1:65
	v_mul_i32_i24_e32 v31, 0x400, v31
	v_and_b32_e32 v13, 0xfffffc00, v13
	v_sub_u32_e32 v0, v0, v31
	v_add_u32_e32 v36, v13, v0
	v_ashrrev_i32_e32 v37, 31, v36
	s_waitcnt lgkmcnt(0)
	v_mul_f32_e32 v0, v18, v32
	v_mul_f32_e32 v13, v19, v33
	v_lshlrev_b64 v[18:19], 12, v[36:37]
	v_lshl_add_u64 v[18:19], v[14:15], 0, v[18:19]
	v_cvt_pk_bf16_f32 v0, v0, v13
	global_store_dword v[18:19], v0, off

.LBB0_917:
	v_ashrrev_i32_e32 v13, 31, v0
	v_lshrrev_b32_e32 v13, 25, v13
	v_add_u32_e32 v13, v0, v13
	ds_read2_b32 v[18:19], v30 offset1:65
	v_lshlrev_b32_e32 v31, 1, v13
	v_and_b32_e32 v13, 0xffffff80, v13
	v_and_b32_e32 v31, 0xffffff00, v31
	v_sub_u32_e32 v0, v0, v13
	v_add_u32_e32 v32, v31, v0
	v_ashrrev_i32_e32 v33, 31, v32
	s_waitcnt lgkmcnt(0)
	v_mul_f32_e32 v0, v16, v18
	v_mul_f32_e32 v13, v17, v19
	v_lshlrev_b64 v[16:17], 11, v[32:33]
	v_lshl_add_u64 v[14:15], v[14:15], 0, v[16:17]
	v_cvt_pk_bf16_f32 v0, v0, v13
	global_store_dword v[14:15], v0, off

.LBB0_925:
	v_ashrrev_i32_e32 v13, 31, v0
	v_lshrrev_b32_e32 v13, 25, v13
	v_add_u32_e32 v13, v0, v13
	ds_read2_b32 v[32:33], v24 offset1:65
	v_lshlrev_b32_e32 v31, 1, v13
	v_and_b32_e32 v13, 0xffffff80, v13
	v_and_b32_e32 v31, 0xffffff00, v31
	v_sub_u32_e32 v0, v0, v13
	v_add_u32_e32 v36, v31, v0
	v_ashrrev_i32_e32 v37, 31, v36
	s_waitcnt vmcnt(0) lgkmcnt(0)
	v_mov_b64_e32 v[50:51], v[18:19]
	v_mul_f32_e32 v0, v18, v32
	v_mul_f32_e32 v13, v19, v33
	v_lshlrev_b64 v[18:19], 11, v[36:37]
	v_lshl_add_u64 v[18:19], v[14:15], 0, v[18:19]
	v_cvt_pk_bf16_f32 v0, v0, v13
	global_store_dword v[18:19], v0, off
.LBB0_926:
	s_or_b64 exec, exec, s[12:13]
	v_add_u32_e32 v0, s14, v25
	v_cmp_gt_i32_e32 vcc, s59, v0
	s_and_saveexec_b64 s[12:13], vcc
	s_cbranch_execz .LBB0_931
	s_andn2_b64 vcc, exec, s[8:9]
	s_cbranch_vccnz .LBB0_929
	v_mov_b64_e32 v[18:19], v[50:51]
	s_branch .LBB0_930

.LBB0_930:
	v_ashrrev_i32_e32 v13, 31, v0
	v_lshrrev_b32_e32 v13, 25, v13
	v_add_u32_e32 v13, v0, v13
	ds_read2_b32 v[32:33], v26 offset1:65
	v_lshlrev_b32_e32 v31, 1, v13
	v_and_b32_e32 v13, 0xffffff80, v13
	v_and_b32_e32 v31, 0xffffff00, v31
	v_sub_u32_e32 v0, v0, v13
	v_add_u32_e32 v36, v31, v0
	v_ashrrev_i32_e32 v37, 31, v36
	s_waitcnt lgkmcnt(0)
	v_mul_f32_e32 v0, v18, v32
	v_mul_f32_e32 v13, v19, v33
	v_lshlrev_b64 v[18:19], 11, v[36:37]
	v_lshl_add_u64 v[18:19], v[14:15], 0, v[18:19]
	v_cvt_pk_bf16_f32 v0, v0, v13
	global_store_dword v[18:19], v0, off
.LBB0_931:
	s_or_b64 exec, exec, s[12:13]
	v_add_u32_e32 v0, s14, v27
	v_cmp_gt_i32_e32 vcc, s59, v0
	s_and_saveexec_b64 s[12:13], vcc
	s_cbranch_execz .LBB0_936
	s_andn2_b64 vcc, exec, s[8:9]
	s_cbranch_vccnz .LBB0_934
	v_mov_b64_e32 v[18:19], v[50:51]
	s_branch .LBB0_935

.LBB0_935:
	v_ashrrev_i32_e32 v13, 31, v0
	v_lshrrev_b32_e32 v13, 25, v13
	v_add_u32_e32 v13, v0, v13
	ds_read2_b32 v[32:33], v28 offset1:65
	v_lshlrev_b32_e32 v31, 1, v13
	v_and_b32_e32 v13, 0xffffff80, v13
	v_and_b32_e32 v31, 0xffffff00, v31
	v_sub_u32_e32 v0, v0, v13
	v_add_u32_e32 v36, v31, v0
	v_ashrrev_i32_e32 v37, 31, v36
	s_waitcnt lgkmcnt(0)
	v_mul_f32_e32 v0, v18, v32
	v_mul_f32_e32 v13, v19, v33
	v_lshlrev_b64 v[18:19], 11, v[36:37]
	v_lshl_add_u64 v[18:19], v[14:15], 0, v[18:19]
	v_cvt_pk_bf16_f32 v0, v0, v13
	global_store_dword v[18:19], v0, off

.LBB0_942:
	v_ashrrev_i32_e32 v13, 31, v0
	v_lshrrev_b32_e32 v13, 25, v13
	v_add_u32_e32 v13, v0, v13
	ds_read2_b32 v[18:19], v30 offset1:65
	v_lshlrev_b32_e32 v31, 1, v13
	v_and_b32_e32 v13, 0xffffff80, v13
	v_and_b32_e32 v31, 0xffffff00, v31
	v_sub_u32_e32 v0, v0, v13
	s_movk_i32 s14, 0x80
	v_add3_u32 v32, v0, v31, s14
	v_ashrrev_i32_e32 v33, 31, v32
	s_waitcnt lgkmcnt(0)
	v_mul_f32_e32 v0, v16, v18
	v_mul_f32_e32 v13, v17, v19
	v_lshlrev_b64 v[16:17], 11, v[32:33]
	v_lshl_add_u64 v[14:15], v[14:15], 0, v[16:17]
	v_cvt_pk_bf16_f32 v0, v0, v13
	global_store_dword v[14:15], v0, off

.LBB0_950:
	v_ashrrev_i32_e32 v13, 31, v0
	v_lshrrev_b32_e32 v13, 25, v13
	v_add_u32_e32 v13, v0, v13
	ds_read2_b32 v[32:33], v24 offset1:65
	v_lshlrev_b32_e32 v31, 1, v13
	v_and_b32_e32 v13, 0xffffff80, v13
	v_and_b32_e32 v31, 0xffffff00, v31
	v_sub_u32_e32 v0, v0, v13
	s_movk_i32 s15, 0x80
	v_add3_u32 v36, v0, v31, s15
	v_ashrrev_i32_e32 v37, 31, v36
	s_waitcnt vmcnt(0) lgkmcnt(0)
	v_mov_b64_e32 v[50:51], v[18:19]
	v_mul_f32_e32 v0, v18, v32
	v_mul_f32_e32 v13, v19, v33
	v_lshlrev_b64 v[18:19], 11, v[36:37]
	v_lshl_add_u64 v[18:19], v[14:15], 0, v[18:19]
	v_cvt_pk_bf16_f32 v0, v0, v13
	global_store_dword v[18:19], v0, off

.LBB0_955:
	v_ashrrev_i32_e32 v13, 31, v0
	v_lshrrev_b32_e32 v13, 25, v13
	v_add_u32_e32 v13, v0, v13
	ds_read2_b32 v[32:33], v26 offset1:65
	v_lshlrev_b32_e32 v31, 1, v13
	v_and_b32_e32 v13, 0xffffff80, v13
	v_and_b32_e32 v31, 0xffffff00, v31
	v_sub_u32_e32 v0, v0, v13
	s_movk_i32 s15, 0x80
	v_add3_u32 v36, v0, v31, s15
	v_ashrrev_i32_e32 v37, 31, v36
	s_waitcnt lgkmcnt(0)
	v_mul_f32_e32 v0, v18, v32
	v_mul_f32_e32 v13, v19, v33
	v_lshlrev_b64 v[18:19], 11, v[36:37]
	v_lshl_add_u64 v[18:19], v[14:15], 0, v[18:19]
	v_cvt_pk_bf16_f32 v0, v0, v13
	global_store_dword v[18:19], v0, off

.LBB0_960:
	v_ashrrev_i32_e32 v13, 31, v0
	v_lshrrev_b32_e32 v13, 25, v13
	v_add_u32_e32 v13, v0, v13
	ds_read2_b32 v[32:33], v28 offset1:65
	v_lshlrev_b32_e32 v31, 1, v13
	v_and_b32_e32 v13, 0xffffff80, v13
	v_and_b32_e32 v31, 0xffffff00, v31
	v_sub_u32_e32 v0, v0, v13
	s_movk_i32 s15, 0x80
	v_add3_u32 v36, v0, v31, s15
	v_ashrrev_i32_e32 v37, 31, v36
	s_waitcnt lgkmcnt(0)
	v_mul_f32_e32 v0, v18, v32
	v_mul_f32_e32 v13, v19, v33
	v_lshlrev_b64 v[18:19], 11, v[36:37]
	v_lshl_add_u64 v[18:19], v[14:15], 0, v[18:19]
	v_cvt_pk_bf16_f32 v0, v0, v13
	global_store_dword v[18:19], v0, off

.LBB0_1087:
	v_readlane_b32 s2, v253, 50
	v_readlane_b32 s3, v253, 51
	global_load_dword v0, v1, s[28:29] sc1
	v_readlane_b32 s5, v254, 33
	s_mov_b64 s[6:7], -1
	s_waitcnt lgkmcnt(0)
	s_nop 0
	global_load_dword v2, v1, s[2:3] sc1
	v_readlane_b32 s2, v253, 52
	v_readlane_b32 s3, v253, 53
	s_nop 0
	s_nop 0
	s_nop 2
	global_load_dword v3, v1, s[2:3] sc1
	v_readlane_b32 s2, v253, 54
	v_readlane_b32 s3, v253, 55
	s_nop 0
	s_nop 0
	s_nop 2
	global_load_dword v4, v1, s[2:3] sc1
	v_readlane_b32 s2, v253, 56
	v_readlane_b32 s3, v253, 57
	s_nop 0
	s_nop 0
	s_nop 2
	global_load_dword v5, v1, s[2:3] sc1
	v_readlane_b32 s2, v253, 58
	v_readlane_b32 s3, v253, 59
	s_nop 0
	s_nop 0
	s_nop 2
	global_load_dword v6, v1, s[2:3] sc1
	v_readlane_b32 s2, v253, 60
	v_readlane_b32 s3, v253, 61
	s_nop 0
	s_nop 0
	s_nop 2
	global_load_dword v7, v1, s[2:3] sc1
	v_readlane_b32 s2, v253, 62
	v_readlane_b32 s3, v253, 63
	s_nop 0
	s_nop 0
	s_nop 2
	global_load_dword v8, v1, s[2:3] sc1
	v_readlane_b32 s2, v254, 0
	v_readlane_b32 s3, v254, 1
	s_nop 0
	s_nop 0
	s_nop 2
	global_load_dword v9, v1, s[2:3] sc1
	v_readlane_b32 s2, v254, 2
	v_readlane_b32 s3, v254, 3
	s_nop 0
	s_nop 0
	s_nop 2
	global_load_dword v10, v1, s[2:3] sc1
	v_readlane_b32 s2, v254, 4
	v_readlane_b32 s3, v254, 5
	s_nop 0
	s_nop 0
	s_nop 2
	global_load_dword v11, v1, s[2:3] sc1
	v_readlane_b32 s2, v254, 6
	v_readlane_b32 s3, v254, 7
	s_nop 0
	s_nop 0
	s_nop 2
	global_load_dword v12, v1, s[2:3] sc1
	v_readlane_b32 s2, v254, 8
	v_readlane_b32 s3, v254, 9
	s_nop 0
	s_nop 0
	s_nop 2
	global_load_dword v13, v1, s[2:3] sc1
	v_readlane_b32 s2, v254, 10
	v_readlane_b32 s3, v254, 11
	s_nop 0
	s_nop 0
	s_nop 2
	global_load_dword v14, v1, s[2:3] sc1
	v_readlane_b32 s2, v254, 12
	v_readlane_b32 s3, v254, 13
	s_nop 0
	s_nop 0
	s_nop 2
	global_load_dword v15, v1, s[2:3] sc1
	v_readlane_b32 s2, v254, 14
	v_readlane_b32 s3, v254, 15
	s_nop 0
	s_nop 0
	s_nop 2
	global_load_dword v16, v1, s[2:3] sc1
	s_mov_b64 s[2:3], -1
	s_nop 0
	s_nop 0
	s_waitcnt vmcnt(0)
	v_add_u32_e32 v17, v2, v0
	v_add_u32_e32 v17, v17, v3
	v_add_u32_e32 v17, v17, v4
	v_add_u32_e32 v17, v17, v5
	v_add_u32_e32 v17, v17, v6
	v_add_u32_e32 v17, v17, v7
	v_add_u32_e32 v17, v17, v8
	v_add_u32_e32 v17, v17, v9
	v_add_u32_e32 v17, v17, v10
	v_add_u32_e32 v17, v17, v11
	v_add_u32_e32 v17, v17, v12
	v_add_u32_e32 v17, v17, v13
	v_add_u32_e32 v17, v17, v14
	v_add_u32_e32 v17, v17, v15
	v_add_u32_e32 v17, v17, v16
	v_cmp_eq_u32_e32 vcc, s5, v17
	s_cbranch_vccnz .LBB0_1086
	s_and_b32 s2, s4, 0xff
	s_cmp_eq_u32 s2, 0
	s_mov_b64 s[2:3], -1
	s_mov_b64 s[8:9], -1
	s_sleep 1
	s_cbranch_scc0 .LBB0_1091
	v_readlane_b32 s2, v253, 48
	v_readlane_b32 s3, v253, 49
	s_nop 4
	global_load_dword v17, v1, s[2:3] sc1
	s_waitcnt vmcnt(0)
	v_cmp_eq_u32_e32 vcc, 0, v17
	s_cbranch_vccnz .LBB0_1093
	s_mov_b64 s[8:9], 0
	s_mov_b64 s[2:3], -1
